# nt cache policy on write-once outputs: P1 f32 K/V output stores, P7 y stores and once-read x2/partial loads; on top of v35
# baseline (speedup 1.0000x reference)
.LBB0_106:
	s_lshl_b32 s10, s10, 8
	s_and_b32 s10, s10, 0x700
	s_mul_hi_i32 s21, s11, 0x2100000
	s_mul_i32 s11, s11, 0x2100000
	v_or_b32_e32 v150, s10, v158
	s_add_u32 s10, s47, s11
	s_addc_u32 s11, s48, s21
	v_lshlrev_b32_e32 v138, 1, v150
	v_lshl_add_u64 v[154:155], s[10:11], 0, v[138:139]
	v_lshlrev_b64 v[174:175], 12, v[152:153]
	s_cmp_lg_u64 s[30:31], 0
	v_lshlrev_b32_e32 v138, 2, v150
	v_lshl_add_u64 v[178:179], v[154:155], 0, v[174:175]
	v_cvt_pk_bf16_f32 v174, v126, v127
	v_cvt_pk_bf16_f32 v175, v128, v129
	v_cvt_pk_bf16_f32 v176, v122, v123
	v_cvt_pk_bf16_f32 v177, v124, v125
	s_cselect_b64 s[28:29], -1, 0
	s_cmp_eq_u64 s[30:31], 0
	v_lshl_add_u64 v[150:151], s[30:31], 0, v[138:139]
	global_store_dwordx4 v[178:179], v[174:177], off
	s_nop 1
	v_cvt_pk_bf16_f32 v174, v118, v119
	v_cvt_pk_bf16_f32 v175, v120, v121
	v_cvt_pk_bf16_f32 v176, v114, v115
	v_cvt_pk_bf16_f32 v177, v116, v117
	global_store_dwordx4 v[178:179], v[174:177], off offset:256
	s_cbranch_scc1 .LBB0_108
	s_nop 0
	v_lshlrev_b64 v[174:175], 13, v[152:153]
	v_lshl_add_u64 v[174:175], v[150:151], 0, v[174:175]
	global_store_dwordx4 v[174:175], v[126:129], off nt
	global_store_dwordx4 v[174:175], v[122:125], off offset:16 nt
	global_store_dwordx4 v[174:175], v[118:121], off offset:512 nt
	global_store_dwordx4 v[174:175], v[114:117], off offset:528 nt

.LBB0_110:
	v_lshlrev_b64 v[116:117], 12, v[114:115]
	v_lshl_add_u64 v[120:121], v[154:155], 0, v[116:117]
	v_cvt_pk_bf16_f32 v116, v110, v111
	v_cvt_pk_bf16_f32 v117, v112, v113
	v_cvt_pk_bf16_f32 v118, v106, v107
	v_cvt_pk_bf16_f32 v119, v108, v109
	v_cndmask_b32_e64 v122, 0, 1, s[28:29]
	global_store_dwordx4 v[120:121], v[116:119], off
	v_cmp_ne_u32_e64 s[10:11], 1, v122
	s_andn2_b64 vcc, exec, s[28:29]
	v_cvt_pk_bf16_f32 v116, v102, v103
	v_cvt_pk_bf16_f32 v117, v104, v105
	v_cvt_pk_bf16_f32 v118, v98, v99
	v_cvt_pk_bf16_f32 v119, v100, v101
	global_store_dwordx4 v[120:121], v[116:119], off offset:256
	s_cbranch_vccnz .LBB0_112
	v_lshlrev_b64 v[114:115], 13, v[114:115]
	v_lshl_add_u64 v[114:115], v[150:151], 0, v[114:115]
	global_store_dwordx4 v[114:115], v[110:113], off nt
	global_store_dwordx4 v[114:115], v[106:109], off offset:16 nt
	global_store_dwordx4 v[114:115], v[102:105], off offset:512 nt
	global_store_dwordx4 v[114:115], v[98:101], off offset:528 nt

.LBB0_114:
	v_lshlrev_b64 v[100:101], 12, v[98:99]
	v_lshl_add_u64 v[104:105], v[154:155], 0, v[100:101]
	v_cvt_pk_bf16_f32 v100, v94, v95
	v_cvt_pk_bf16_f32 v101, v96, v97
	v_cvt_pk_bf16_f32 v102, v90, v91
	v_cvt_pk_bf16_f32 v103, v92, v93
	global_store_dwordx4 v[104:105], v[100:103], off
	s_and_b64 vcc, exec, s[10:11]
	s_nop 0
	v_cvt_pk_bf16_f32 v100, v86, v87
	v_cvt_pk_bf16_f32 v101, v88, v89
	v_cvt_pk_bf16_f32 v102, v82, v83
	v_cvt_pk_bf16_f32 v103, v84, v85
	global_store_dwordx4 v[104:105], v[100:103], off offset:256
	s_cbranch_vccnz .LBB0_116
	v_lshlrev_b64 v[98:99], 13, v[98:99]
	v_lshl_add_u64 v[98:99], v[150:151], 0, v[98:99]
	global_store_dwordx4 v[98:99], v[94:97], off nt
	global_store_dwordx4 v[98:99], v[90:93], off offset:16 nt
	global_store_dwordx4 v[98:99], v[86:89], off offset:512 nt
	global_store_dwordx4 v[98:99], v[82:85], off offset:528 nt

.LBB0_118:
	v_lshlrev_b64 v[84:85], 12, v[82:83]
	v_lshl_add_u64 v[88:89], v[154:155], 0, v[84:85]
	v_cvt_pk_bf16_f32 v84, v78, v79
	v_cvt_pk_bf16_f32 v85, v80, v81
	v_cvt_pk_bf16_f32 v86, v74, v75
	v_cvt_pk_bf16_f32 v87, v76, v77
	global_store_dwordx4 v[88:89], v[84:87], off
	s_and_b64 vcc, exec, s[10:11]
	s_nop 0
	v_cvt_pk_bf16_f32 v84, v70, v71
	v_cvt_pk_bf16_f32 v85, v72, v73
	v_cvt_pk_bf16_f32 v86, v66, v67
	v_cvt_pk_bf16_f32 v87, v68, v69
	global_store_dwordx4 v[88:89], v[84:87], off offset:256
	s_cbranch_vccnz .LBB0_120
	v_lshlrev_b64 v[82:83], 13, v[82:83]
	v_lshl_add_u64 v[82:83], v[150:151], 0, v[82:83]
	global_store_dwordx4 v[82:83], v[78:81], off nt
	global_store_dwordx4 v[82:83], v[74:77], off offset:16 nt
	global_store_dwordx4 v[82:83], v[70:73], off offset:512 nt
	global_store_dwordx4 v[82:83], v[66:69], off offset:528 nt

.LBB0_122:
	v_lshlrev_b64 v[68:69], 12, v[66:67]
	v_lshl_add_u64 v[72:73], v[154:155], 0, v[68:69]
	v_cvt_pk_bf16_f32 v68, v62, v63
	v_cvt_pk_bf16_f32 v69, v64, v65
	v_cvt_pk_bf16_f32 v70, v58, v59
	v_cvt_pk_bf16_f32 v71, v60, v61
	global_store_dwordx4 v[72:73], v[68:71], off
	s_and_b64 vcc, exec, s[10:11]
	s_nop 0
	v_cvt_pk_bf16_f32 v68, v54, v55
	v_cvt_pk_bf16_f32 v69, v56, v57
	v_cvt_pk_bf16_f32 v70, v50, v51
	v_cvt_pk_bf16_f32 v71, v52, v53
	global_store_dwordx4 v[72:73], v[68:71], off offset:256
	s_cbranch_vccnz .LBB0_124
	v_lshlrev_b64 v[66:67], 13, v[66:67]
	v_lshl_add_u64 v[66:67], v[150:151], 0, v[66:67]
	global_store_dwordx4 v[66:67], v[62:65], off nt
	global_store_dwordx4 v[66:67], v[58:61], off offset:16 nt
	global_store_dwordx4 v[66:67], v[54:57], off offset:512 nt
	global_store_dwordx4 v[66:67], v[50:53], off offset:528 nt

.LBB0_126:
	v_lshlrev_b64 v[52:53], 12, v[50:51]
	v_lshl_add_u64 v[56:57], v[154:155], 0, v[52:53]
	v_cvt_pk_bf16_f32 v52, v46, v47
	v_cvt_pk_bf16_f32 v53, v48, v49
	v_cvt_pk_bf16_f32 v54, v42, v43
	v_cvt_pk_bf16_f32 v55, v44, v45
	global_store_dwordx4 v[56:57], v[52:55], off
	s_and_b64 vcc, exec, s[10:11]
	s_nop 0
	v_cvt_pk_bf16_f32 v52, v38, v39
	v_cvt_pk_bf16_f32 v53, v40, v41
	v_cvt_pk_bf16_f32 v54, v34, v35
	v_cvt_pk_bf16_f32 v55, v36, v37
	global_store_dwordx4 v[56:57], v[52:55], off offset:256
	s_cbranch_vccnz .LBB0_128
	v_lshlrev_b64 v[50:51], 13, v[50:51]
	v_lshl_add_u64 v[50:51], v[150:151], 0, v[50:51]
	global_store_dwordx4 v[50:51], v[46:49], off nt
	global_store_dwordx4 v[50:51], v[42:45], off offset:16 nt
	global_store_dwordx4 v[50:51], v[38:41], off offset:512 nt
	global_store_dwordx4 v[50:51], v[34:37], off offset:528 nt

.LBB0_130:
	v_lshlrev_b64 v[36:37], 12, v[34:35]
	v_lshl_add_u64 v[40:41], v[154:155], 0, v[36:37]
	v_cvt_pk_bf16_f32 v36, v30, v31
	v_cvt_pk_bf16_f32 v37, v32, v33
	v_cvt_pk_bf16_f32 v38, v26, v27
	v_cvt_pk_bf16_f32 v39, v28, v29
	global_store_dwordx4 v[40:41], v[36:39], off
	s_and_b64 vcc, exec, s[10:11]
	s_nop 0
	v_cvt_pk_bf16_f32 v36, v22, v23
	v_cvt_pk_bf16_f32 v37, v24, v25
	v_cvt_pk_bf16_f32 v38, v18, v19
	v_cvt_pk_bf16_f32 v39, v20, v21
	global_store_dwordx4 v[40:41], v[36:39], off offset:256
	s_cbranch_vccnz .LBB0_132
	v_lshlrev_b64 v[34:35], 13, v[34:35]
	v_lshl_add_u64 v[34:35], v[150:151], 0, v[34:35]
	global_store_dwordx4 v[34:35], v[30:33], off nt
	global_store_dwordx4 v[34:35], v[26:29], off offset:16 nt
	global_store_dwordx4 v[34:35], v[22:25], off offset:512 nt
	global_store_dwordx4 v[34:35], v[18:21], off offset:528 nt

.LBB0_134:
	v_lshlrev_b64 v[20:21], 12, v[18:19]
	v_lshl_add_u64 v[24:25], v[154:155], 0, v[20:21]
	v_cvt_pk_bf16_f32 v20, v14, v15
	v_cvt_pk_bf16_f32 v21, v16, v17
	v_cvt_pk_bf16_f32 v22, v10, v11
	v_cvt_pk_bf16_f32 v23, v12, v13
	global_store_dwordx4 v[24:25], v[20:23], off
	s_and_b64 vcc, exec, s[10:11]
	s_nop 0
	v_cvt_pk_bf16_f32 v20, v6, v7
	v_cvt_pk_bf16_f32 v21, v8, v9
	v_cvt_pk_bf16_f32 v22, v2, v3
	v_cvt_pk_bf16_f32 v23, v4, v5
	global_store_dwordx4 v[24:25], v[20:23], off offset:256
	s_cbranch_vccnz .LBB0_136
	v_lshlrev_b64 v[18:19], 13, v[18:19]
	v_lshl_add_u64 v[18:19], v[150:151], 0, v[18:19]
	global_store_dwordx4 v[18:19], v[14:17], off nt
	global_store_dwordx4 v[18:19], v[10:13], off offset:16 nt
	global_store_dwordx4 v[18:19], v[6:9], off offset:512 nt
	global_store_dwordx4 v[18:19], v[2:5], off offset:528 nt

.LBB0_864:
	s_mov_b64 s[2:3], s[0:1]
	s_mov_b64 s[28:29], s[0:1]
	s_load_dwordx2 s[2:3], s[2:3], 0xa0
	s_load_dwordx2 s[28:29], s[28:29], 0xa0
	s_ashr_i32 s17, s16, 31
	s_lshl_b64 s[30:31], s[16:17], 14
	s_waitcnt lgkmcnt(0)
	s_add_u32 s28, s28, s30
	s_addc_u32 s29, s29, s31
	v_lshl_add_u64 v[0:1], s[28:29], 0, v[98:99]
	v_add_co_u32_e32 v100, vcc, s18, v0
	v_lshl_add_u64 v[2:3], v[0:1], 0, s[12:13]
	s_nop 0
	v_addc_co_u32_e32 v101, vcc, 0, v1, vcc
	v_add_co_u32_e32 v104, vcc, 0x39002000, v0
	global_load_dwordx4 v[56:59], v[2:3], off offset:1024 nt
	global_load_dwordx4 v[52:55], v[2:3], off offset:2048 nt
	global_load_dwordx4 v[44:47], v[100:101], off nt
	global_load_dwordx4 v[40:43], v[100:101], off offset:1024 nt
	global_load_dwordx4 v[36:39], v[100:101], off offset:2048 nt
	global_load_dwordx4 v[32:35], v[100:101], off offset:3072 nt
	v_addc_co_u32_e32 v105, vcc, 0, v1, vcc
	v_add_co_u32_e32 v106, vcc, 0x39003000, v0
	global_load_dwordx4 v[48:51], v[2:3], off offset:3072 nt
	global_load_dwordx4 v[28:31], v[104:105], off nt
	global_load_dwordx4 v[24:27], v[104:105], off offset:1024 nt
	global_load_dwordx4 v[20:23], v[104:105], off offset:2048 nt
	v_addc_co_u32_e32 v107, vcc, 0, v1, vcc
	global_load_dwordx4 v[16:19], v[104:105], off offset:3072 nt
	global_load_dwordx4 v[12:15], v[106:107], off nt
	global_load_dwordx4 v[8:11], v[106:107], off offset:1024 nt
	global_load_dwordx4 v[4:7], v[106:107], off offset:2048 nt
	global_load_dwordx4 v[60:63], v[100:101], off offset:-4096 nt
	global_load_dwordx4 v[0:3], v[106:107], off offset:3072 nt
	v_lshl_add_u64 v[100:101], s[2:3], 0, v[96:97]
	s_mov_b64 s[2:3], 0
.LBB0_865:
	v_lshl_add_u64 v[104:105], v[100:101], 0, s[2:3]
	v_add_co_u32_e32 v120, vcc, s19, v104
	s_add_u32 s2, s2, 0x400000
	s_nop 0
	v_addc_co_u32_e32 v121, vcc, 0, v105, vcc
	v_add_co_u32_e32 v132, vcc, s20, v104
	s_addc_u32 s3, s3, 0
	s_nop 0
	v_addc_co_u32_e32 v133, vcc, 0, v105, vcc
	v_add_co_u32_e32 v148, vcc, s21, v104
	s_cmp_lg_u32 s2, 0x1000000
	s_nop 0
	v_addc_co_u32_e32 v149, vcc, 0, v105, vcc
	v_add_co_u32_e32 v164, vcc, s22, v104
	s_nop 1
	v_addc_co_u32_e32 v165, vcc, 0, v105, vcc
	global_load_dwordx4 v[104:107], v[132:133], off offset:-4096
	global_load_dwordx4 v[108:111], v[120:121], off offset:1024
	global_load_dwordx4 v[112:115], v[120:121], off offset:2048
	global_load_dwordx4 v[116:119], v[120:121], off offset:3072
	s_nop 0
	global_load_dwordx4 v[120:123], v[132:133], off
	global_load_dwordx4 v[124:127], v[132:133], off offset:1024
	global_load_dwordx4 v[128:131], v[132:133], off offset:2048
	s_nop 0
	global_load_dwordx4 v[132:135], v[132:133], off offset:3072 nt
	s_nop 0
	global_load_dwordx4 v[136:139], v[164:165], off offset:-4096 nt
	global_load_dwordx4 v[140:143], v[148:149], off offset:1024 nt
	global_load_dwordx4 v[144:147], v[148:149], off offset:2048 nt
	s_nop 0
	global_load_dwordx4 v[148:151], v[148:149], off offset:3072 nt
	s_nop 0
	global_load_dwordx4 v[152:155], v[164:165], off nt
	global_load_dwordx4 v[156:159], v[164:165], off offset:1024 nt
	global_load_dwordx4 v[160:163], v[164:165], off offset:2048 nt
	s_nop 0
	global_load_dwordx4 v[164:167], v[164:165], off offset:3072
	s_waitcnt vmcnt(15)
	v_pk_add_f32 v[62:63], v[106:107], v[62:63]
	v_pk_add_f32 v[60:61], v[104:105], v[60:61]
	s_waitcnt vmcnt(14)
	v_pk_add_f32 v[58:59], v[110:111], v[58:59]
	v_pk_add_f32 v[56:57], v[108:109], v[56:57]
	s_waitcnt vmcnt(13)
	v_pk_add_f32 v[54:55], v[114:115], v[54:55]
	v_pk_add_f32 v[52:53], v[112:113], v[52:53]
	s_waitcnt vmcnt(12)
	v_pk_add_f32 v[50:51], v[118:119], v[50:51]
	v_pk_add_f32 v[48:49], v[116:117], v[48:49]
	s_waitcnt vmcnt(11)
	v_pk_add_f32 v[46:47], v[122:123], v[46:47]
	v_pk_add_f32 v[44:45], v[120:121], v[44:45]
	s_waitcnt vmcnt(10)
	v_pk_add_f32 v[42:43], v[126:127], v[42:43]
	v_pk_add_f32 v[40:41], v[124:125], v[40:41]
	s_waitcnt vmcnt(9)
	v_pk_add_f32 v[38:39], v[130:131], v[38:39]
	v_pk_add_f32 v[36:37], v[128:129], v[36:37]
	s_waitcnt vmcnt(8)
	v_pk_add_f32 v[34:35], v[134:135], v[34:35]
	v_pk_add_f32 v[32:33], v[132:133], v[32:33]
	s_waitcnt vmcnt(7)
	v_pk_add_f32 v[30:31], v[138:139], v[30:31]
	v_pk_add_f32 v[28:29], v[136:137], v[28:29]
	s_waitcnt vmcnt(6)
	v_pk_add_f32 v[26:27], v[142:143], v[26:27]
	v_pk_add_f32 v[24:25], v[140:141], v[24:25]
	s_waitcnt vmcnt(5)
	v_pk_add_f32 v[22:23], v[146:147], v[22:23]
	v_pk_add_f32 v[20:21], v[144:145], v[20:21]
	s_waitcnt vmcnt(4)
	v_pk_add_f32 v[18:19], v[150:151], v[18:19]
	v_pk_add_f32 v[16:17], v[148:149], v[16:17]
	s_waitcnt vmcnt(3)
	v_pk_add_f32 v[14:15], v[154:155], v[14:15]
	v_pk_add_f32 v[12:13], v[152:153], v[12:13]
	s_waitcnt vmcnt(2)
	v_pk_add_f32 v[10:11], v[158:159], v[10:11]
	v_pk_add_f32 v[8:9], v[156:157], v[8:9]
	s_waitcnt vmcnt(1)
	v_pk_add_f32 v[6:7], v[162:163], v[6:7]
	v_pk_add_f32 v[4:5], v[160:161], v[4:5]
	s_waitcnt vmcnt(0)
	v_pk_add_f32 v[2:3], v[166:167], v[2:3]
	v_pk_add_f32 v[0:1], v[164:165], v[0:1]
	s_cbranch_scc1 .LBB0_865
	global_load_dwordx4 v[168:171], v[70:71], off
	global_load_dwordx4 v[172:175], v[70:71], off offset:1024
	global_load_dwordx4 v[176:179], v[70:71], off offset:2048
	global_load_dwordx4 v[180:183], v[70:71], off offset:3072
	global_load_dwordx4 v[184:187], v[72:73], off
	global_load_dwordx4 v[188:191], v[74:75], off
	global_load_dwordx4 v[192:195], v[76:77], off
	global_load_dwordx4 v[196:199], v[78:79], off
	global_load_dwordx4 v[200:203], v[80:81], off
	global_load_dwordx4 v[204:207], v[82:83], off
	global_load_dwordx4 v[208:211], v[84:85], off
	global_load_dwordx4 v[212:215], v[86:87], off
	global_load_dwordx4 v[216:219], v[88:89], off
	global_load_dwordx4 v[220:223], v[90:91], off
	global_load_dwordx4 v[224:227], v[92:93], off
	global_load_dwordx4 v[228:231], v[94:95], off
	v_mul_f32_e32 v100, v61, v61
	v_mul_f32_e32 v101, v63, v63
	v_fmac_f32_e32 v100, v60, v60
	v_fmac_f32_e32 v101, v62, v62
	v_add_f32_e32 v100, v100, v101
	v_mul_f32_e32 v101, v57, v57
	v_mul_f32_e32 v104, v59, v59
	v_fmac_f32_e32 v101, v56, v56
	v_fmac_f32_e32 v104, v58, v58
	v_add_f32_e32 v101, v101, v104
	v_add_f32_e32 v100, v100, v101
	v_mul_f32_e32 v101, v53, v53
	v_mul_f32_e32 v104, v55, v55
	v_fmac_f32_e32 v101, v52, v52
	v_fmac_f32_e32 v104, v54, v54
	v_add_f32_e32 v101, v101, v104
	v_add_f32_e32 v100, v100, v101
	v_mul_f32_e32 v101, v49, v49
	v_mul_f32_e32 v104, v51, v51
	v_fmac_f32_e32 v101, v48, v48
	v_fmac_f32_e32 v104, v50, v50
	v_add_f32_e32 v101, v101, v104
	v_add_f32_e32 v100, v100, v101
	v_mul_f32_e32 v101, v45, v45
	v_mul_f32_e32 v104, v47, v47
	v_fmac_f32_e32 v101, v44, v44
	v_fmac_f32_e32 v104, v46, v46
	v_add_f32_e32 v101, v101, v104
	v_add_f32_e32 v100, v100, v101
	v_mul_f32_e32 v101, v41, v41
	v_mul_f32_e32 v104, v43, v43
	v_fmac_f32_e32 v101, v40, v40
	v_fmac_f32_e32 v104, v42, v42
	v_add_f32_e32 v101, v101, v104
	v_add_f32_e32 v100, v100, v101
	v_mul_f32_e32 v101, v37, v37
	v_mul_f32_e32 v104, v39, v39
	v_fmac_f32_e32 v101, v36, v36
	v_fmac_f32_e32 v104, v38, v38
	v_add_f32_e32 v101, v101, v104
	v_add_f32_e32 v100, v100, v101
	v_mul_f32_e32 v101, v33, v33
	v_mul_f32_e32 v104, v35, v35
	v_fmac_f32_e32 v101, v32, v32
	v_fmac_f32_e32 v104, v34, v34
	v_add_f32_e32 v101, v101, v104
	v_add_f32_e32 v100, v100, v101
	v_mul_f32_e32 v101, v29, v29
	v_mul_f32_e32 v104, v31, v31
	v_fmac_f32_e32 v101, v28, v28
	v_fmac_f32_e32 v104, v30, v30
	v_add_f32_e32 v101, v101, v104
	v_add_f32_e32 v100, v100, v101
	v_mul_f32_e32 v101, v25, v25
	v_mul_f32_e32 v104, v27, v27
	v_fmac_f32_e32 v101, v24, v24
	v_fmac_f32_e32 v104, v26, v26
	v_add_f32_e32 v101, v101, v104
	v_add_f32_e32 v100, v100, v101
	v_mul_f32_e32 v101, v21, v21
	v_mul_f32_e32 v104, v23, v23
	v_fmac_f32_e32 v101, v20, v20
	v_fmac_f32_e32 v104, v22, v22
	v_add_f32_e32 v101, v101, v104
	v_add_f32_e32 v100, v100, v101
	v_mul_f32_e32 v101, v17, v17
	v_mul_f32_e32 v104, v19, v19
	v_fmac_f32_e32 v101, v16, v16
	v_fmac_f32_e32 v104, v18, v18
	v_add_f32_e32 v101, v101, v104
	v_add_f32_e32 v100, v100, v101
	v_mul_f32_e32 v101, v13, v13
	v_mul_f32_e32 v104, v15, v15
	v_fmac_f32_e32 v101, v12, v12
	v_fmac_f32_e32 v104, v14, v14
	v_add_f32_e32 v101, v101, v104
	v_add_f32_e32 v100, v100, v101
	v_mul_f32_e32 v101, v9, v9
	v_mul_f32_e32 v104, v11, v11
	v_fmac_f32_e32 v101, v8, v8
	v_fmac_f32_e32 v104, v10, v10
	v_add_f32_e32 v101, v101, v104
	v_add_f32_e32 v100, v100, v101
	v_mul_f32_e32 v101, v5, v5
	v_mul_f32_e32 v104, v7, v7
	v_fmac_f32_e32 v101, v4, v4
	v_fmac_f32_e32 v104, v6, v6
	v_add_f32_e32 v101, v101, v104
	v_add_f32_e32 v100, v100, v101
	v_mul_f32_e32 v101, v1, v1
	v_mul_f32_e32 v104, v3, v3
	v_fmac_f32_e32 v101, v0, v0
	v_fmac_f32_e32 v104, v2, v2
	v_add_f32_e32 v101, v101, v104
	v_add_f32_e32 v100, v100, v101
	v_and_b32_e32 v101, 64, v103
	v_add_u32_e32 v101, 64, v101
	v_xor_b32_e32 v104, 1, v103
	v_cmp_lt_i32_e32 vcc, v104, v101
	v_lshl_add_u64 v[96:97], v[96:97], 0, s[10:11]
	s_nop 0
	v_cndmask_b32_e32 v104, v103, v104, vcc
	v_lshlrev_b32_e32 v104, 2, v104
	ds_bpermute_b32 v104, v104, v100
	s_waitcnt lgkmcnt(0)
	v_add_f32_e32 v100, v100, v104
	v_xor_b32_e32 v104, 2, v103
	v_cmp_lt_i32_e32 vcc, v104, v101
	s_nop 1
	v_cndmask_b32_e32 v104, v103, v104, vcc
	v_lshlrev_b32_e32 v104, 2, v104
	ds_bpermute_b32 v104, v104, v100
	s_waitcnt lgkmcnt(0)
	v_add_f32_e32 v100, v100, v104
	v_xor_b32_e32 v104, 4, v103
	v_cmp_lt_i32_e32 vcc, v104, v101
	s_nop 1
	v_cndmask_b32_e32 v108, v103, v104, vcc
	v_lshlrev_b32_e32 v108, 2, v108
	ds_bpermute_b32 v108, v108, v100
	s_waitcnt lgkmcnt(0)
	v_add_f32_e32 v100, v100, v108
	v_xor_b32_e32 v108, 8, v103
	v_cmp_lt_i32_e32 vcc, v108, v101
	s_nop 1
	v_cndmask_b32_e32 v108, v103, v108, vcc
	v_lshlrev_b32_e32 v108, 2, v108
	ds_bpermute_b32 v108, v108, v100
	s_waitcnt lgkmcnt(0)
	v_add_f32_e32 v100, v100, v108
	v_xor_b32_e32 v108, 16, v103
	v_cmp_lt_i32_e32 vcc, v108, v101
	s_nop 1
	v_cndmask_b32_e32 v108, v103, v108, vcc
	v_lshlrev_b32_e32 v108, 2, v108
	ds_bpermute_b32 v108, v108, v100
	s_waitcnt lgkmcnt(0)
	v_add_f32_e32 v100, v100, v108
	v_xor_b32_e32 v108, 32, v103
	v_cmp_lt_i32_e32 vcc, v108, v101
	s_nop 1
	v_cndmask_b32_e32 v101, v103, v108, vcc
	v_lshlrev_b32_e32 v101, 2, v101
	ds_bpermute_b32 v101, v101, v100
	s_waitcnt lgkmcnt(0)
	v_add_f32_e32 v100, v100, v101
	v_fmamk_f32 v100, v100, 0x39800000, v65
	v_mul_f32_e32 v101, 0x4f800000, v100
	v_cmp_gt_f32_e32 vcc, s23, v100
	s_nop 1
	v_cndmask_b32_e32 v100, v100, v101, vcc
	v_sqrt_f32_e32 v101, v100
	s_nop 0
	v_add_u32_e32 v108, -1, v101
	v_fma_f32 v109, -v108, v101, v100
	v_cmp_ge_f32_e64 s[2:3], 0, v109
	v_add_u32_e32 v109, 1, v101
	s_nop 0
	v_cndmask_b32_e64 v108, v101, v108, s[2:3]
	v_fma_f32 v101, -v109, v101, v100
	v_cmp_lt_f32_e64 s[2:3], 0, v101
	s_nop 1
	v_cndmask_b32_e64 v101, v108, v109, s[2:3]
	v_mul_f32_e32 v108, 0x37800000, v101
	v_cndmask_b32_e32 v101, v101, v108, vcc
	v_cmp_class_f32_e32 vcc, v100, v102
	s_nop 1
	v_cndmask_b32_e32 v100, v101, v100, vcc
	v_div_scale_f32 v101, s[2:3], v100, v100, 1.0
	v_rcp_f32_e32 v108, v101
	s_lshl_b64 s[2:3], s[16:17], 14
	s_add_i32 s16, s16, s84
	s_cmpk_gt_i32 s16, 0xff
	v_fma_f32 v109, -v101, v108, 1.0
	v_fmac_f32_e32 v108, v109, v108
	v_div_scale_f32 v109, vcc, 1.0, v100, 1.0
	v_mul_f32_e32 v110, v109, v108
	v_fma_f32 v111, -v101, v110, v109
	v_fmac_f32_e32 v110, v111, v108
	v_fma_f32 v101, -v101, v110, v109
	v_div_fmas_f32 v101, v101, v108, v110
	v_div_fixup_f32 v100, v101, v100, 1.0
	v_add_f32_e32 v100, v67, v100
	v_lshl_add_u64 v[108:109], v[68:69], 0, s[2:3]
	v_add_co_u32_e32 v104, vcc, s24, v108
	s_nop 1
	v_addc_co_u32_e32 v105, vcc, 0, v109, vcc
	v_lshl_add_u64 v[106:107], v[108:109], 0, s[14:15]
	v_add_co_u32_e32 v232, vcc, s26, v108
	s_nop 1
	v_addc_co_u32_e32 v233, vcc, 0, v109, vcc
	v_add_co_u32_e32 v234, vcc, s25, v108
	s_nop 1
	v_addc_co_u32_e32 v235, vcc, 0, v109, vcc
	v_pk_mul_f32 v[60:61], v[100:101], v[60:61] op_sel_hi:[0,1]
	v_pk_mul_f32 v[62:63], v[100:101], v[62:63] op_sel_hi:[0,1]
	v_pk_mul_f32 v[58:59], v[100:101], v[58:59] op_sel_hi:[0,1]
	v_pk_mul_f32 v[56:57], v[100:101], v[56:57] op_sel_hi:[0,1]
	v_pk_mul_f32 v[54:55], v[100:101], v[54:55] op_sel_hi:[0,1]
	v_pk_mul_f32 v[52:53], v[100:101], v[52:53] op_sel_hi:[0,1]
	v_pk_mul_f32 v[50:51], v[100:101], v[50:51] op_sel_hi:[0,1]
	v_pk_mul_f32 v[48:49], v[100:101], v[48:49] op_sel_hi:[0,1]
	v_pk_mul_f32 v[46:47], v[100:101], v[46:47] op_sel_hi:[0,1]
	v_pk_mul_f32 v[44:45], v[100:101], v[44:45] op_sel_hi:[0,1]
	v_pk_mul_f32 v[42:43], v[100:101], v[42:43] op_sel_hi:[0,1]
	v_pk_mul_f32 v[40:41], v[100:101], v[40:41] op_sel_hi:[0,1]
	v_pk_mul_f32 v[38:39], v[100:101], v[38:39] op_sel_hi:[0,1]
	v_pk_mul_f32 v[36:37], v[100:101], v[36:37] op_sel_hi:[0,1]
	v_pk_mul_f32 v[34:35], v[100:101], v[34:35] op_sel_hi:[0,1]
	v_pk_mul_f32 v[32:33], v[100:101], v[32:33] op_sel_hi:[0,1]
	v_pk_mul_f32 v[30:31], v[100:101], v[30:31] op_sel_hi:[0,1]
	v_pk_mul_f32 v[28:29], v[100:101], v[28:29] op_sel_hi:[0,1]
	v_pk_mul_f32 v[26:27], v[100:101], v[26:27] op_sel_hi:[0,1]
	v_pk_mul_f32 v[24:25], v[100:101], v[24:25] op_sel_hi:[0,1]
	v_pk_mul_f32 v[22:23], v[100:101], v[22:23] op_sel_hi:[0,1]
	v_pk_mul_f32 v[20:21], v[100:101], v[20:21] op_sel_hi:[0,1]
	v_pk_mul_f32 v[18:19], v[100:101], v[18:19] op_sel_hi:[0,1]
	v_pk_mul_f32 v[16:17], v[100:101], v[16:17] op_sel_hi:[0,1]
	v_pk_mul_f32 v[14:15], v[100:101], v[14:15] op_sel_hi:[0,1]
	v_pk_mul_f32 v[12:13], v[100:101], v[12:13] op_sel_hi:[0,1]
	v_pk_mul_f32 v[10:11], v[100:101], v[10:11] op_sel_hi:[0,1]
	v_pk_mul_f32 v[8:9], v[100:101], v[8:9] op_sel_hi:[0,1]
	v_pk_mul_f32 v[6:7], v[100:101], v[6:7] op_sel_hi:[0,1]
	v_pk_mul_f32 v[4:5], v[100:101], v[4:5] op_sel_hi:[0,1]
	v_pk_mul_f32 v[2:3], v[100:101], v[2:3] op_sel_hi:[0,1]
	v_pk_mul_f32 v[0:1], v[100:101], v[0:1] op_sel_hi:[0,1]
	s_waitcnt vmcnt(0)
	v_pk_mul_f32 v[60:61], v[60:61], v[168:169]
	v_pk_mul_f32 v[62:63], v[62:63], v[170:171]
	global_store_dwordx4 v[104:105], v[60:63], off offset:-4096 nt
	v_pk_mul_f32 v[56:57], v[56:57], v[172:173]
	v_pk_mul_f32 v[58:59], v[58:59], v[174:175]
	global_store_dwordx4 v[106:107], v[56:59], off offset:1024 nt
	v_pk_mul_f32 v[52:53], v[52:53], v[176:177]
	v_pk_mul_f32 v[54:55], v[54:55], v[178:179]
	global_store_dwordx4 v[106:107], v[52:55], off offset:2048 nt
	v_pk_mul_f32 v[48:49], v[48:49], v[180:181]
	v_pk_mul_f32 v[50:51], v[50:51], v[182:183]
	global_store_dwordx4 v[106:107], v[48:51], off offset:3072 nt
	v_pk_mul_f32 v[44:45], v[44:45], v[184:185]
	v_pk_mul_f32 v[46:47], v[46:47], v[186:187]
	global_store_dwordx4 v[104:105], v[44:47], off nt
	v_pk_mul_f32 v[40:41], v[40:41], v[188:189]
	v_pk_mul_f32 v[42:43], v[42:43], v[190:191]
	global_store_dwordx4 v[104:105], v[40:43], off offset:1024 nt
	v_pk_mul_f32 v[36:37], v[36:37], v[192:193]
	v_pk_mul_f32 v[38:39], v[38:39], v[194:195]
	global_store_dwordx4 v[104:105], v[36:39], off offset:2048 nt
	v_pk_mul_f32 v[32:33], v[32:33], v[196:197]
	v_pk_mul_f32 v[34:35], v[34:35], v[198:199]
	global_store_dwordx4 v[104:105], v[32:35], off offset:3072 nt
	v_pk_mul_f32 v[28:29], v[28:29], v[200:201]
	v_pk_mul_f32 v[30:31], v[30:31], v[202:203]
	global_store_dwordx4 v[232:233], v[28:31], off offset:-4096 nt
	v_pk_mul_f32 v[24:25], v[24:25], v[204:205]
	v_pk_mul_f32 v[26:27], v[26:27], v[206:207]
	global_store_dwordx4 v[234:235], v[24:27], off offset:1024 nt
	v_pk_mul_f32 v[20:21], v[20:21], v[208:209]
	v_pk_mul_f32 v[22:23], v[22:23], v[210:211]
	global_store_dwordx4 v[234:235], v[20:23], off offset:2048 nt
	v_pk_mul_f32 v[16:17], v[16:17], v[212:213]
	v_pk_mul_f32 v[18:19], v[18:19], v[214:215]
	global_store_dwordx4 v[234:235], v[16:19], off offset:3072 nt
	v_pk_mul_f32 v[12:13], v[12:13], v[216:217]
	v_pk_mul_f32 v[14:15], v[14:15], v[218:219]
	global_store_dwordx4 v[232:233], v[12:15], off nt
	v_pk_mul_f32 v[8:9], v[8:9], v[220:221]
	v_pk_mul_f32 v[10:11], v[10:11], v[222:223]
	global_store_dwordx4 v[232:233], v[8:11], off offset:1024 nt
	v_pk_mul_f32 v[4:5], v[4:5], v[224:225]
	v_pk_mul_f32 v[6:7], v[6:7], v[226:227]
	global_store_dwordx4 v[232:233], v[4:7], off offset:2048 nt
	v_pk_mul_f32 v[0:1], v[0:1], v[228:229]
	v_pk_mul_f32 v[2:3], v[2:3], v[230:231]
	global_store_dwordx4 v[232:233], v[0:3], off offset:3072 nt
	s_cbranch_scc0 .LBB0_864
.LBB0_867:
	s_cmpk_gt_i32 s82, 0x1fff
	s_cbranch_scc1 .LBB0_870
	v_lshlrev_b32_e32 v0, 5, v66
	v_mov_b32_e32 v1, 0
	s_waitcnt lgkmcnt(0)
	v_lshl_add_u64 v[2:3], s[8:9], 0, v[0:1]
	s_mov_b64 s[2:3], 0x1000
	v_lshl_add_u64 v[4:5], v[2:3], 0, s[2:3]
	s_mov_b64 s[2:3], 0x1800
	v_lshl_add_u64 v[6:7], v[2:3], 0, s[2:3]
	s_mov_b64 s[2:3], 0x2000
	v_lshl_add_u64 v[8:9], v[2:3], 0, s[2:3]
	s_mov_b64 s[2:3], 0x2800
	v_lshl_add_u64 v[10:11], v[2:3], 0, s[2:3]
	s_mov_b64 s[2:3], 0x3000
	v_lshl_add_u64 v[12:13], v[2:3], 0, s[2:3]
	s_mov_b64 s[2:3], 0x3800
	s_ashr_i32 s83, s82, 31
	v_lshl_add_u64 v[14:15], v[2:3], 0, s[2:3]
	s_lshl_b64 s[2:3], s[82:83], 2
	s_add_u32 s2, s6, s2
	s_addc_u32 s3, s7, s3
	s_add_u32 s2, s2, 0x20000
	s_addc_u32 s3, s3, 0
	s_ashr_i32 s85, s84, 31
	s_load_dwordx2 s[0:1], s[0:1], 0xa0
	s_lshl_b64 s[6:7], s[84:85], 2
	s_lshl_b64 s[8:9], s[82:83], 14
	s_add_u32 s4, s4, s8
	s_addc_u32 s5, s5, s9
	v_lshl_add_u64 v[16:17], s[4:5], 0, v[0:1]
	s_mov_b64 s[4:5], 0x3810
	v_lshl_add_u64 v[16:17], v[16:17], 0, s[4:5]
	s_lshl_b64 s[4:5], s[84:85], 14
	s_lshl_b64 s[8:9], s[82:83], 13
	s_waitcnt lgkmcnt(0)
	s_add_u32 s0, s0, s8
	v_mov_b32_e32 v65, v1
	s_addc_u32 s1, s1, s9
	v_lshl_add_u64 v[18:19], s[0:1], 0, v[64:65]
	s_mov_b64 s[0:1], 0x28c01c00
	v_lshl_add_u64 v[18:19], v[18:19], 0, s[0:1]
	s_lshl_b64 s[8:9], s[84:85], 13
	v_mov_b32_e32 v20, 0x358637bd
	s_mov_b32 s10, 0xf800000
	v_mov_b32_e32 v21, 0x260
	s_movk_i32 s11, 0xf000
	s_movk_i32 s12, 0xd000
	s_movk_i32 s13, 0xe000
	global_load_dwordx4 v[68:71], v[2:3], off
	global_load_dwordx4 v[72:75], v[2:3], off offset:16
	global_load_dwordx4 v[76:79], v[2:3], off offset:2048
	global_load_dwordx4 v[80:83], v[2:3], off offset:2064
	global_load_dwordx4 v[84:87], v[4:5], off
	global_load_dwordx4 v[88:91], v[4:5], off offset:16
	global_load_dwordx4 v[92:95], v[6:7], off
	global_load_dwordx4 v[96:99], v[6:7], off offset:16
	global_load_dwordx4 v[100:103], v[8:9], off
	global_load_dwordx4 v[104:107], v[8:9], off offset:16
	global_load_dwordx4 v[108:111], v[10:11], off
	global_load_dwordx4 v[112:115], v[10:11], off offset:16
	global_load_dwordx4 v[116:119], v[12:13], off
	global_load_dwordx4 v[120:123], v[12:13], off offset:16
	global_load_dwordx4 v[124:127], v[14:15], off
	global_load_dwordx4 v[128:131], v[14:15], off offset:16
	global_load_dword v0, v1, s[2:3]
	v_add_co_u32_e32 v34, vcc, s11, v18
	s_nop 1
	v_addc_co_u32_e32 v35, vcc, -1, v19, vcc
	global_load_dwordx4 v[132:135], v[34:35], off offset:-3072 nt
	global_load_dwordx4 v[136:139], v[34:35], off offset:-2048 nt
	global_load_dwordx4 v[140:143], v[34:35], off offset:-1024 nt
	global_load_dwordx4 v[144:147], v[18:19], off offset:-4096 nt
	global_load_dwordx4 v[148:151], v[18:19], off offset:-3072 nt
	global_load_dwordx4 v[152:155], v[18:19], off offset:-2048 nt
	global_load_dwordx4 v[156:159], v[18:19], off offset:-1024 nt
	global_load_dwordx4 v[160:163], v[18:19], off nt
	s_waitcnt vmcnt(0)
.Lp7_row:
	s_waitcnt vmcnt(16)
	v_fmamk_f32 v46, v0, 0x39800000, v20
	v_lshlrev_b32_e32 v164, 16, v132
	v_and_b32_e32 v165, 0xffff0000, v132
	v_lshlrev_b32_e32 v166, 16, v133
	v_and_b32_e32 v167, 0xffff0000, v133
	v_lshlrev_b32_e32 v168, 16, v134
	v_and_b32_e32 v169, 0xffff0000, v134
	v_lshlrev_b32_e32 v170, 16, v135
	v_and_b32_e32 v171, 0xffff0000, v135
	v_lshlrev_b32_e32 v172, 16, v136
	v_and_b32_e32 v173, 0xffff0000, v136
	v_lshlrev_b32_e32 v174, 16, v137
	v_and_b32_e32 v175, 0xffff0000, v137
	v_lshlrev_b32_e32 v176, 16, v138
	v_and_b32_e32 v177, 0xffff0000, v138
	v_lshlrev_b32_e32 v178, 16, v139
	v_and_b32_e32 v179, 0xffff0000, v139
	v_lshlrev_b32_e32 v180, 16, v140
	v_and_b32_e32 v181, 0xffff0000, v140
	v_lshlrev_b32_e32 v182, 16, v141
	v_and_b32_e32 v183, 0xffff0000, v141
	v_lshlrev_b32_e32 v184, 16, v142
	v_and_b32_e32 v185, 0xffff0000, v142
	v_lshlrev_b32_e32 v186, 16, v143
	v_and_b32_e32 v187, 0xffff0000, v143
	v_lshlrev_b32_e32 v188, 16, v144
	v_and_b32_e32 v189, 0xffff0000, v144
	v_lshlrev_b32_e32 v190, 16, v145
	v_and_b32_e32 v191, 0xffff0000, v145
	v_lshlrev_b32_e32 v192, 16, v146
	v_and_b32_e32 v193, 0xffff0000, v146
	v_lshlrev_b32_e32 v194, 16, v147
	v_and_b32_e32 v195, 0xffff0000, v147
	v_lshlrev_b32_e32 v196, 16, v148
	v_and_b32_e32 v197, 0xffff0000, v148
	v_lshlrev_b32_e32 v198, 16, v149
	v_and_b32_e32 v199, 0xffff0000, v149
	v_lshlrev_b32_e32 v200, 16, v150
	v_and_b32_e32 v201, 0xffff0000, v150
	v_lshlrev_b32_e32 v202, 16, v151
	v_and_b32_e32 v203, 0xffff0000, v151
	v_lshlrev_b32_e32 v204, 16, v152
	v_and_b32_e32 v205, 0xffff0000, v152
	v_lshlrev_b32_e32 v206, 16, v153
	v_and_b32_e32 v207, 0xffff0000, v153
	v_lshlrev_b32_e32 v208, 16, v154
	v_and_b32_e32 v209, 0xffff0000, v154
	v_lshlrev_b32_e32 v210, 16, v155
	v_and_b32_e32 v211, 0xffff0000, v155
	v_lshlrev_b32_e32 v212, 16, v156
	v_and_b32_e32 v213, 0xffff0000, v156
	v_lshlrev_b32_e32 v214, 16, v157
	v_and_b32_e32 v215, 0xffff0000, v157
	v_lshlrev_b32_e32 v216, 16, v158
	v_and_b32_e32 v217, 0xffff0000, v158
	v_lshlrev_b32_e32 v218, 16, v159
	v_and_b32_e32 v219, 0xffff0000, v159
	v_lshlrev_b32_e32 v220, 16, v160
	v_and_b32_e32 v221, 0xffff0000, v160
	v_lshlrev_b32_e32 v222, 16, v161
	v_and_b32_e32 v223, 0xffff0000, v161
	v_lshlrev_b32_e32 v224, 16, v162
	v_and_b32_e32 v225, 0xffff0000, v162
	v_lshlrev_b32_e32 v226, 16, v163
	v_and_b32_e32 v227, 0xffff0000, v163
	s_add_i32 s82, s82, s84
	s_add_u32 s2, s2, s6
	s_addc_u32 s3, s3, s7
	v_lshl_add_u64 v[18:19], v[18:19], 0, s[8:9]
	s_cmpk_lt_i32 s82, 0x2000
	s_cbranch_scc0 .Lp7_nopf
	global_load_dword v0, v1, s[2:3]
	v_add_co_u32_e32 v34, vcc, s11, v18
	s_nop 1
	v_addc_co_u32_e32 v35, vcc, -1, v19, vcc
	global_load_dwordx4 v[132:135], v[34:35], off offset:-3072 nt
	global_load_dwordx4 v[136:139], v[34:35], off offset:-2048 nt
	global_load_dwordx4 v[140:143], v[34:35], off offset:-1024 nt
	global_load_dwordx4 v[144:147], v[18:19], off offset:-4096 nt
	global_load_dwordx4 v[148:151], v[18:19], off offset:-3072 nt
	global_load_dwordx4 v[152:155], v[18:19], off offset:-2048 nt
	global_load_dwordx4 v[156:159], v[18:19], off offset:-1024 nt
	global_load_dwordx4 v[160:163], v[18:19], off nt
.Lp7_nopf:
	v_add_co_u32_e32 v36, vcc, s12, v16
	s_nop 1
	v_addc_co_u32_e32 v37, vcc, -1, v17, vcc
	v_add_co_u32_e32 v38, vcc, s13, v16
	s_nop 1
	v_addc_co_u32_e32 v39, vcc, -1, v17, vcc
	v_add_co_u32_e32 v40, vcc, s11, v16
	s_nop 1
	v_addc_co_u32_e32 v41, vcc, -1, v17, vcc
	v_mul_f32_e32 v48, 0x4f800000, v46
	v_cmp_gt_f32_e32 vcc, s10, v46
	s_nop 1
	v_cndmask_b32_e32 v46, v46, v48, vcc
	v_sqrt_f32_e32 v48, v46
	s_nop 0
	v_add_u32_e32 v49, -1, v48
	v_add_u32_e32 v50, 1, v48
	v_fma_f32 v51, -v49, v48, v46
	v_fma_f32 v52, -v50, v48, v46
	v_cmp_ge_f32_e64 s[0:1], 0, v51
	s_nop 1
	v_cndmask_b32_e64 v48, v48, v49, s[0:1]
	v_cmp_lt_f32_e64 s[0:1], 0, v52
	s_nop 1
	v_cndmask_b32_e64 v48, v48, v50, s[0:1]
	v_mul_f32_e32 v49, 0x37800000, v48
	v_cndmask_b32_e32 v48, v48, v49, vcc
	v_cmp_class_f32_e32 vcc, v46, v21
	s_nop 1
	v_cndmask_b32_e32 v46, v48, v46, vcc
	v_div_scale_f32 v48, s[0:1], v46, v46, 1.0
	v_rcp_f32_e32 v50, v48
	v_div_scale_f32 v49, vcc, 1.0, v46, 1.0
	v_fma_f32 v51, -v48, v50, 1.0
	v_fmac_f32_e32 v50, v51, v50
	v_mul_f32_e32 v51, v49, v50
	v_fma_f32 v52, -v48, v51, v49
	v_fmac_f32_e32 v51, v52, v50
	v_fma_f32 v48, -v48, v51, v49
	v_div_fmas_f32 v48, v48, v50, v51
	v_div_fixup_f32 v46, v48, v46, 1.0
	v_add_f32_e32 v46, v67, v46
	v_pk_mul_f32 v[164:165], v[46:47], v[164:165] op_sel_hi:[0,1]
	v_pk_mul_f32 v[166:167], v[46:47], v[166:167] op_sel_hi:[0,1]
	v_pk_mul_f32 v[168:169], v[46:47], v[168:169] op_sel_hi:[0,1]
	v_pk_mul_f32 v[170:171], v[46:47], v[170:171] op_sel_hi:[0,1]
	v_pk_mul_f32 v[164:165], v[68:69], v[164:165]
	v_pk_mul_f32 v[166:167], v[70:71], v[166:167]
	v_pk_mul_f32 v[168:169], v[72:73], v[168:169]
	v_pk_mul_f32 v[170:171], v[74:75], v[170:171]
	global_store_dwordx4 v[36:37], v[164:167], off offset:-2064 nt
	global_store_dwordx4 v[36:37], v[168:171], off offset:-2048 nt
	v_pk_mul_f32 v[172:173], v[46:47], v[172:173] op_sel_hi:[0,1]
	v_pk_mul_f32 v[174:175], v[46:47], v[174:175] op_sel_hi:[0,1]
	v_pk_mul_f32 v[176:177], v[46:47], v[176:177] op_sel_hi:[0,1]
	v_pk_mul_f32 v[178:179], v[46:47], v[178:179] op_sel_hi:[0,1]
	v_pk_mul_f32 v[172:173], v[76:77], v[172:173]
	v_pk_mul_f32 v[174:175], v[78:79], v[174:175]
	v_pk_mul_f32 v[176:177], v[80:81], v[176:177]
	v_pk_mul_f32 v[178:179], v[82:83], v[178:179]
	global_store_dwordx4 v[36:37], v[172:175], off offset:-16 nt
	global_store_dwordx4 v[38:39], v[176:179], off offset:-4096 nt
	v_pk_mul_f32 v[180:181], v[46:47], v[180:181] op_sel_hi:[0,1]
	v_pk_mul_f32 v[182:183], v[46:47], v[182:183] op_sel_hi:[0,1]
	v_pk_mul_f32 v[184:185], v[46:47], v[184:185] op_sel_hi:[0,1]
	v_pk_mul_f32 v[186:187], v[46:47], v[186:187] op_sel_hi:[0,1]
	v_pk_mul_f32 v[180:181], v[84:85], v[180:181]
	v_pk_mul_f32 v[182:183], v[86:87], v[182:183]
	v_pk_mul_f32 v[184:185], v[88:89], v[184:185]
	v_pk_mul_f32 v[186:187], v[90:91], v[186:187]
	global_store_dwordx4 v[38:39], v[180:183], off offset:-2064 nt
	global_store_dwordx4 v[38:39], v[184:187], off offset:-2048 nt
	v_pk_mul_f32 v[188:189], v[46:47], v[188:189] op_sel_hi:[0,1]
	v_pk_mul_f32 v[190:191], v[46:47], v[190:191] op_sel_hi:[0,1]
	v_pk_mul_f32 v[192:193], v[46:47], v[192:193] op_sel_hi:[0,1]
	v_pk_mul_f32 v[194:195], v[46:47], v[194:195] op_sel_hi:[0,1]
	v_pk_mul_f32 v[188:189], v[92:93], v[188:189]
	v_pk_mul_f32 v[190:191], v[94:95], v[190:191]
	v_pk_mul_f32 v[192:193], v[96:97], v[192:193]
	v_pk_mul_f32 v[194:195], v[98:99], v[194:195]
	global_store_dwordx4 v[38:39], v[188:191], off offset:-16 nt
	global_store_dwordx4 v[38:39], v[192:195], off nt
	v_pk_mul_f32 v[196:197], v[46:47], v[196:197] op_sel_hi:[0,1]
	v_pk_mul_f32 v[198:199], v[46:47], v[198:199] op_sel_hi:[0,1]
	v_pk_mul_f32 v[200:201], v[46:47], v[200:201] op_sel_hi:[0,1]
	v_pk_mul_f32 v[202:203], v[46:47], v[202:203] op_sel_hi:[0,1]
	v_pk_mul_f32 v[196:197], v[100:101], v[196:197]
	v_pk_mul_f32 v[198:199], v[102:103], v[198:199]
	v_pk_mul_f32 v[200:201], v[104:105], v[200:201]
	v_pk_mul_f32 v[202:203], v[106:107], v[202:203]
	global_store_dwordx4 v[40:41], v[196:199], off offset:-2064 nt
	global_store_dwordx4 v[40:41], v[200:203], off offset:-2048 nt
	v_pk_mul_f32 v[204:205], v[46:47], v[204:205] op_sel_hi:[0,1]
	v_pk_mul_f32 v[206:207], v[46:47], v[206:207] op_sel_hi:[0,1]
	v_pk_mul_f32 v[208:209], v[46:47], v[208:209] op_sel_hi:[0,1]
	v_pk_mul_f32 v[210:211], v[46:47], v[210:211] op_sel_hi:[0,1]
	v_pk_mul_f32 v[204:205], v[108:109], v[204:205]
	v_pk_mul_f32 v[206:207], v[110:111], v[206:207]
	v_pk_mul_f32 v[208:209], v[112:113], v[208:209]
	v_pk_mul_f32 v[210:211], v[114:115], v[210:211]
	global_store_dwordx4 v[40:41], v[204:207], off offset:-16 nt
	global_store_dwordx4 v[16:17], v[208:211], off offset:-4096 nt
	v_pk_mul_f32 v[212:213], v[46:47], v[212:213] op_sel_hi:[0,1]
	v_pk_mul_f32 v[214:215], v[46:47], v[214:215] op_sel_hi:[0,1]
	v_pk_mul_f32 v[216:217], v[46:47], v[216:217] op_sel_hi:[0,1]
	v_pk_mul_f32 v[218:219], v[46:47], v[218:219] op_sel_hi:[0,1]
	v_pk_mul_f32 v[212:213], v[116:117], v[212:213]
	v_pk_mul_f32 v[214:215], v[118:119], v[214:215]
	v_pk_mul_f32 v[216:217], v[120:121], v[216:217]
	v_pk_mul_f32 v[218:219], v[122:123], v[218:219]
	global_store_dwordx4 v[16:17], v[212:215], off offset:-2064 nt
	global_store_dwordx4 v[16:17], v[216:219], off offset:-2048 nt
	v_pk_mul_f32 v[220:221], v[46:47], v[220:221] op_sel_hi:[0,1]
	v_pk_mul_f32 v[222:223], v[46:47], v[222:223] op_sel_hi:[0,1]
	v_pk_mul_f32 v[224:225], v[46:47], v[224:225] op_sel_hi:[0,1]
	v_pk_mul_f32 v[226:227], v[46:47], v[226:227] op_sel_hi:[0,1]
	v_pk_mul_f32 v[220:221], v[124:125], v[220:221]
	v_pk_mul_f32 v[222:223], v[126:127], v[222:223]
	v_pk_mul_f32 v[224:225], v[128:129], v[224:225]
	v_pk_mul_f32 v[226:227], v[130:131], v[226:227]
	global_store_dwordx4 v[16:17], v[220:223], off offset:-16 nt
	global_store_dwordx4 v[16:17], v[224:227], off nt
	v_lshl_add_u64 v[16:17], v[16:17], 0, s[4:5]
	s_cmpk_lt_i32 s82, 0x2000
	s_cbranch_scc1 .Lp7_row
